# v25 plus FFN2-up epilogue with row-norm loads batched up front and no per-row drains
# speedup vs baseline: 1.0123x; 1.0083x over previous
; __device__ __forceinline__ unsigned cvt_pk_bf16(float lo, float hi) { const f32x2 v = {lo, hi}; return __builtin_bit_cast(unsigned, __builtin_convertvector(v, bf16x2_t)); }
; __device__ __forceinline__ float silu_f(float v) { return v * fast_rcp(1.0f + __expf(-v)); }
;     __device__ __forceinline__ void operator()(const f32x4 (&acc)[2][2][4][2], const Unit& u, int wr, int wc, int fr, int fq) const {
;         const int row0 = u.pm * 256 + wr * 64 + fr, col0 = u.pn * 128 + wc * 32 + 8 * fq;
; #pragma unroll
;         for (int ai = 0; ai < 2; ++ai)
; #pragma unroll
;             for (int m = 0; m < 4; ++m) {
;                 bf16_t* rowp = O + (size_t)(row0 + ai * 128 + m * 16) * ldc + col0;
;                 const float rs = ssq ? rsqrtf(ssq[row0 + ai * 128 + m * 16] * (1.0f / DM) + 1e-6f) : 1.0f;
;                 float v[8];
; #pragma unroll
;                 for (int n = 0; n < 2; ++n)
; #pragma unroll
;                     for (int j = 0; j < 4; ++j) v[n * 4 + j] = silu_f(acc[ai][0][m][n][j] * rs) * (acc[ai][1][m][n][j] * rs);
;                 u32x4 w; w.x = cvt_pk_bf16(v[0], v[1]); w.y = cvt_pk_bf16(v[2], v[3]); w.z = cvt_pk_bf16(v[4], v[5]); w.w = cvt_pk_bf16(v[6], v[7]);
;                 *(u32x4*)rowp = w;
;             }
;     }
.LBB0_1436:
	v_lshl_add_u32 v140, s0, 8, v148
	v_ashrrev_i32_e32 v141, 31, v140
	v_lshl_add_u64 v[146:147], v[140:141], 2, s[14:15]
	global_load_dword v230, v[146:147], off
	global_load_dword v231, v[146:147], off offset:64
	global_load_dword v232, v[146:147], off offset:128
	global_load_dword v233, v[146:147], off offset:192
	global_load_dword v234, v[146:147], off offset:512
	global_load_dword v235, v[146:147], off offset:576
	global_load_dword v236, v[146:147], off offset:640
	global_load_dword v237, v[146:147], off offset:704
	v_or_b32_e32 v158, 16, v140
	v_ashrrev_i32_e32 v159, 31, v158
	v_lshl_add_u64 v[160:161], v[158:159], 2, s[14:15]
	v_lshl_or_b32 v144, s1, 7, v150
	v_mov_b64_e32 v[142:143], s[12:13]
	v_ashrrev_i32_e32 v145, 31, v144
	v_mad_i64_i32 v[156:157], s[0:1], v140, s51, v[142:143]
	v_lshlrev_b64 v[144:145], 1, v[144:145]
	v_lshl_add_u64 v[156:157], v[156:157], 0, v[144:145]
	s_waitcnt vmcnt(0)
	v_mov_b32_e32 v141, v230
	v_fmamk_f32 v141, v141, 0x3a000000, v154
	v_mul_f32_e32 v155, 0x4b800000, v141
	v_cmp_gt_f32_e32 vcc, s60, v141
	s_nop 1
	v_cndmask_b32_e32 v141, v141, v155, vcc
	v_rsq_f32_e32 v141, v141
	s_nop 0
	v_mul_f32_e32 v155, 0x45800000, v141
	v_cndmask_b32_e32 v162, v141, v155, vcc
	v_pk_mul_f32 v[124:125], v[124:125], v[162:163] op_sel_hi:[1,0]
	v_pk_mul_f32 v[126:127], v[126:127], v[162:163] op_sel_hi:[1,0]
	v_pk_mul_f32 v[120:121], v[120:121], v[162:163] op_sel_hi:[1,0]
	v_pk_mul_f32 v[122:123], v[122:123], v[162:163] op_sel_hi:[1,0]
	v_pk_mul_f32 v[116:117], v[116:117], v[162:163] op_sel_hi:[1,0]
	v_pk_mul_f32 v[118:119], v[118:119], v[162:163] op_sel_hi:[1,0]
	v_pk_mul_f32 v[112:113], v[112:113], v[162:163] op_sel_hi:[1,0]
	v_pk_mul_f32 v[114:115], v[114:115], v[162:163] op_sel_hi:[1,0]
	v_mul_f32_e32 v141, 0xbfb8aa3b, v124
	v_mul_f32_e32 v155, 0xbfb8aa3b, v125
	v_mul_f32_e32 v159, 0xbfb8aa3b, v126
	v_mul_f32_e32 v162, 0xbfb8aa3b, v127
	v_mul_f32_e32 v163, 0xbfb8aa3b, v120
	v_mul_f32_e32 v164, 0xbfb8aa3b, v121
	v_mul_f32_e32 v165, 0xbfb8aa3b, v122
	v_mul_f32_e32 v166, 0xbfb8aa3b, v123
	v_exp_f32_e32 v141, v141
	v_exp_f32_e32 v155, v155
	v_exp_f32_e32 v159, v159
	v_exp_f32_e32 v162, v162
	v_exp_f32_e32 v163, v163
	v_exp_f32_e32 v164, v164
	v_exp_f32_e32 v165, v165
	v_exp_f32_e32 v166, v166
	v_add_f32_e32 v141, 1.0, v141
	v_add_f32_e32 v155, 1.0, v155
	v_add_f32_e32 v159, 1.0, v159
	v_add_f32_e32 v167, 1.0, v162
	v_add_f32_e32 v168, 1.0, v163
	v_add_f32_e32 v169, 1.0, v164
	v_add_f32_e32 v170, 1.0, v165
	v_add_f32_e32 v171, 1.0, v166
	v_rcp_f32_e32 v162, v141
	v_rcp_f32_e32 v163, v155
	v_rcp_f32_e32 v164, v159
	v_rcp_f32_e32 v165, v167
	v_rcp_f32_e32 v166, v168
	v_rcp_f32_e32 v167, v169
	v_rcp_f32_e32 v168, v170
	v_rcp_f32_e32 v169, v171
	v_pk_mul_f32 v[124:125], v[124:125], v[162:163]
	v_pk_mul_f32 v[126:127], v[126:127], v[164:165]
	v_pk_mul_f32 v[120:121], v[120:121], v[166:167]
	v_pk_mul_f32 v[122:123], v[122:123], v[168:169]
	v_pk_mul_f32 v[116:117], v[116:117], v[124:125]
	v_pk_mul_f32 v[118:119], v[118:119], v[126:127]
	v_pk_mul_f32 v[120:121], v[112:113], v[120:121]
	v_pk_mul_f32 v[122:123], v[114:115], v[122:123]
	v_cvt_pk_bf16_f32 v112, v116, v117
	v_cvt_pk_bf16_f32 v113, v118, v119
	v_cvt_pk_bf16_f32 v114, v120, v121
	v_cvt_pk_bf16_f32 v115, v122, v123
	global_store_dwordx4 v[156:157], v[112:115], off
	global_load_dword v238, v[146:147], off
	s_nop 0
	v_or_b32_e32 v112, 32, v140
	v_mad_i64_i32 v[114:115], s[0:1], v158, s51, v[142:143]
	v_lshl_add_u64 v[114:115], v[114:115], 0, v[144:145]
	s_nop 1
	v_mov_b32_e32 v113, v231
	v_fmamk_f32 v113, v113, 0x3a000000, v154
	v_mul_f32_e32 v116, 0x4b800000, v113
	v_cmp_gt_f32_e32 vcc, s60, v113
	s_nop 1
	v_cndmask_b32_e32 v113, v113, v116, vcc
	v_rsq_f32_e32 v118, v113
	v_ashrrev_i32_e32 v113, 31, v112
	v_lshl_add_u64 v[116:117], v[112:113], 2, s[14:15]
	v_mul_f32_e32 v113, 0x45800000, v118
	v_cndmask_b32_e32 v118, v118, v113, vcc
	v_pk_mul_f32 v[108:109], v[108:109], v[118:119] op_sel_hi:[1,0]
	v_pk_mul_f32 v[110:111], v[110:111], v[118:119] op_sel_hi:[1,0]
	v_pk_mul_f32 v[104:105], v[104:105], v[118:119] op_sel_hi:[1,0]
	v_pk_mul_f32 v[106:107], v[106:107], v[118:119] op_sel_hi:[1,0]
	v_pk_mul_f32 v[100:101], v[100:101], v[118:119] op_sel_hi:[1,0]
	v_pk_mul_f32 v[102:103], v[102:103], v[118:119] op_sel_hi:[1,0]
	v_pk_mul_f32 v[96:97], v[96:97], v[118:119] op_sel_hi:[1,0]
	v_pk_mul_f32 v[98:99], v[98:99], v[118:119] op_sel_hi:[1,0]
	v_mul_f32_e32 v113, 0xbfb8aa3b, v108
	v_mul_f32_e32 v118, 0xbfb8aa3b, v109
	v_mul_f32_e32 v119, 0xbfb8aa3b, v110
	v_mul_f32_e32 v120, 0xbfb8aa3b, v111
	v_mul_f32_e32 v121, 0xbfb8aa3b, v104
	v_mul_f32_e32 v122, 0xbfb8aa3b, v105
	v_mul_f32_e32 v123, 0xbfb8aa3b, v106
	v_mul_f32_e32 v124, 0xbfb8aa3b, v107
	v_exp_f32_e32 v113, v113
	v_exp_f32_e32 v118, v118
	v_exp_f32_e32 v119, v119
	v_exp_f32_e32 v120, v120
	v_exp_f32_e32 v121, v121
	v_exp_f32_e32 v122, v122
	v_exp_f32_e32 v123, v123
	v_exp_f32_e32 v124, v124
	v_add_f32_e32 v113, 1.0, v113
	v_add_f32_e32 v125, 1.0, v118
	v_add_f32_e32 v126, 1.0, v119
	v_add_f32_e32 v127, 1.0, v120
	v_add_f32_e32 v141, 1.0, v121
	v_add_f32_e32 v155, 1.0, v122
	v_add_f32_e32 v156, 1.0, v123
	v_add_f32_e32 v157, 1.0, v124
	v_rcp_f32_e32 v118, v113
	v_rcp_f32_e32 v119, v125
	v_rcp_f32_e32 v120, v126
	v_rcp_f32_e32 v121, v127
	v_rcp_f32_e32 v122, v141
	v_rcp_f32_e32 v123, v155
	v_rcp_f32_e32 v124, v156
	v_rcp_f32_e32 v125, v157
	v_pk_mul_f32 v[108:109], v[108:109], v[118:119]
	v_pk_mul_f32 v[110:111], v[110:111], v[120:121]
	v_pk_mul_f32 v[104:105], v[104:105], v[122:123]
	v_pk_mul_f32 v[106:107], v[106:107], v[124:125]
	v_pk_mul_f32 v[100:101], v[100:101], v[108:109]
	v_pk_mul_f32 v[102:103], v[102:103], v[110:111]
; __device__ __forceinline__ unsigned cvt_pk_bf16(float lo, float hi) { const f32x2 v = {lo, hi}; return __builtin_bit_cast(unsigned, __builtin_convertvector(v, bf16x2_t)); }
; __device__ __forceinline__ float silu_f(float v) { return v * fast_rcp(1.0f + __expf(-v)); }
;     __device__ __forceinline__ void operator()(const f32x4 (&acc)[2][2][4][2], const Unit& u, int wr, int wc, int fr, int fq) const {
;         const int row0 = u.pm * 256 + wr * 64 + fr, col0 = u.pn * 128 + wc * 32 + 8 * fq;
; #pragma unroll
;         for (int ai = 0; ai < 2; ++ai)
; #pragma unroll
;             for (int m = 0; m < 4; ++m) {
;                 bf16_t* rowp = O + (size_t)(row0 + ai * 128 + m * 16) * ldc + col0;
;                 const float rs = ssq ? rsqrtf(ssq[row0 + ai * 128 + m * 16] * (1.0f / DM) + 1e-6f) : 1.0f;
;                 float v[8];
; #pragma unroll
;                 for (int n = 0; n < 2; ++n)
; #pragma unroll
;                     for (int j = 0; j < 4; ++j) v[n * 4 + j] = silu_f(acc[ai][0][m][n][j] * rs) * (acc[ai][1][m][n][j] * rs);
;                 u32x4 w; w.x = cvt_pk_bf16(v[0], v[1]); w.y = cvt_pk_bf16(v[2], v[3]); w.z = cvt_pk_bf16(v[4], v[5]); w.w = cvt_pk_bf16(v[6], v[7]);
;                 *(u32x4*)rowp = w;
;             }
;     }
	v_pk_mul_f32 v[104:105], v[96:97], v[104:105]
	v_pk_mul_f32 v[106:107], v[98:99], v[106:107]
	v_cvt_pk_bf16_f32 v96, v100, v101
	v_cvt_pk_bf16_f32 v97, v102, v103
	v_cvt_pk_bf16_f32 v98, v104, v105
	v_cvt_pk_bf16_f32 v99, v106, v107
	global_store_dwordx4 v[114:115], v[96:99], off
	global_load_dword v238, v[146:147], off
	s_nop 0
	v_or_b32_e32 v96, 48, v140
	v_mad_i64_i32 v[98:99], s[0:1], v112, s51, v[142:143]
	v_lshl_add_u64 v[98:99], v[98:99], 0, v[144:145]
	s_nop 1
	v_mov_b32_e32 v97, v232
	v_fmamk_f32 v97, v97, 0x3a000000, v154
	v_mul_f32_e32 v100, 0x4b800000, v97
	v_cmp_gt_f32_e32 vcc, s60, v97
	s_nop 1
	v_cndmask_b32_e32 v97, v97, v100, vcc
	v_rsq_f32_e32 v102, v97
	v_ashrrev_i32_e32 v97, 31, v96
	v_lshl_add_u64 v[100:101], v[96:97], 2, s[14:15]
	v_mul_f32_e32 v97, 0x45800000, v102
	v_cndmask_b32_e32 v102, v102, v97, vcc
	v_pk_mul_f32 v[92:93], v[92:93], v[102:103] op_sel_hi:[1,0]
	v_pk_mul_f32 v[94:95], v[94:95], v[102:103] op_sel_hi:[1,0]
	v_pk_mul_f32 v[88:89], v[88:89], v[102:103] op_sel_hi:[1,0]
	v_pk_mul_f32 v[90:91], v[90:91], v[102:103] op_sel_hi:[1,0]
	v_pk_mul_f32 v[84:85], v[84:85], v[102:103] op_sel_hi:[1,0]
	v_pk_mul_f32 v[86:87], v[86:87], v[102:103] op_sel_hi:[1,0]
	v_pk_mul_f32 v[80:81], v[80:81], v[102:103] op_sel_hi:[1,0]
	v_pk_mul_f32 v[82:83], v[82:83], v[102:103] op_sel_hi:[1,0]
	v_mul_f32_e32 v97, 0xbfb8aa3b, v92
	v_mul_f32_e32 v102, 0xbfb8aa3b, v93
	v_mul_f32_e32 v103, 0xbfb8aa3b, v94
	v_mul_f32_e32 v104, 0xbfb8aa3b, v95
	v_mul_f32_e32 v105, 0xbfb8aa3b, v88
	v_mul_f32_e32 v106, 0xbfb8aa3b, v89
	v_mul_f32_e32 v107, 0xbfb8aa3b, v90
	v_mul_f32_e32 v108, 0xbfb8aa3b, v91
	v_exp_f32_e32 v97, v97
	v_exp_f32_e32 v102, v102
	v_exp_f32_e32 v103, v103
	v_exp_f32_e32 v104, v104
	v_exp_f32_e32 v105, v105
	v_exp_f32_e32 v106, v106
	v_exp_f32_e32 v107, v107
	v_exp_f32_e32 v108, v108
	v_add_f32_e32 v97, 1.0, v97
	v_add_f32_e32 v109, 1.0, v102
	v_add_f32_e32 v110, 1.0, v103
	v_add_f32_e32 v111, 1.0, v104
	v_add_f32_e32 v112, 1.0, v105
	v_add_f32_e32 v113, 1.0, v106
	v_add_f32_e32 v114, 1.0, v107
	v_add_f32_e32 v115, 1.0, v108
	v_rcp_f32_e32 v102, v97
	v_rcp_f32_e32 v103, v109
	v_rcp_f32_e32 v104, v110
	v_rcp_f32_e32 v105, v111
	v_rcp_f32_e32 v106, v112
	v_rcp_f32_e32 v107, v113
	v_rcp_f32_e32 v108, v114
	v_rcp_f32_e32 v109, v115
	v_pk_mul_f32 v[92:93], v[92:93], v[102:103]
	v_pk_mul_f32 v[94:95], v[94:95], v[104:105]
	v_pk_mul_f32 v[88:89], v[88:89], v[106:107]
	v_pk_mul_f32 v[90:91], v[90:91], v[108:109]
	v_pk_mul_f32 v[84:85], v[84:85], v[92:93]
	v_pk_mul_f32 v[86:87], v[86:87], v[94:95]
	v_pk_mul_f32 v[88:89], v[80:81], v[88:89]
	v_pk_mul_f32 v[90:91], v[82:83], v[90:91]
	v_cvt_pk_bf16_f32 v80, v84, v85
	v_cvt_pk_bf16_f32 v81, v86, v87
	v_cvt_pk_bf16_f32 v82, v88, v89
	v_cvt_pk_bf16_f32 v83, v90, v91
	global_store_dwordx4 v[98:99], v[80:83], off
	global_load_dword v238, v[146:147], off
	s_nop 1
	v_mov_b32_e32 v80, v233
	v_fmamk_f32 v80, v80, 0x3a000000, v154
	v_mul_f32_e32 v81, 0x4b800000, v80
	v_cmp_gt_f32_e32 vcc, s60, v80
	s_nop 1
	v_cndmask_b32_e32 v80, v80, v81, vcc
	v_rsq_f32_e32 v82, v80
	v_mad_i64_i32 v[80:81], s[0:1], v96, s51, v[142:143]
	v_lshl_add_u64 v[80:81], v[80:81], 0, v[144:145]
	v_mul_f32_e32 v83, 0x45800000, v82
	v_cndmask_b32_e32 v82, v82, v83, vcc
	v_pk_mul_f32 v[76:77], v[76:77], v[82:83] op_sel_hi:[1,0]
	v_pk_mul_f32 v[78:79], v[78:79], v[82:83] op_sel_hi:[1,0]
	v_pk_mul_f32 v[72:73], v[72:73], v[82:83] op_sel_hi:[1,0]
	v_pk_mul_f32 v[74:75], v[74:75], v[82:83] op_sel_hi:[1,0]
	v_pk_mul_f32 v[68:69], v[68:69], v[82:83] op_sel_hi:[1,0]
	v_pk_mul_f32 v[70:71], v[70:71], v[82:83] op_sel_hi:[1,0]
	v_pk_mul_f32 v[64:65], v[64:65], v[82:83] op_sel_hi:[1,0]
	v_pk_mul_f32 v[66:67], v[66:67], v[82:83] op_sel_hi:[1,0]
	v_mul_f32_e32 v82, 0xbfb8aa3b, v76
	v_mul_f32_e32 v83, 0xbfb8aa3b, v77
	v_mul_f32_e32 v84, 0xbfb8aa3b, v78
	v_mul_f32_e32 v85, 0xbfb8aa3b, v79
	v_mul_f32_e32 v86, 0xbfb8aa3b, v72
	v_mul_f32_e32 v87, 0xbfb8aa3b, v73
	v_mul_f32_e32 v88, 0xbfb8aa3b, v74
	v_mul_f32_e32 v89, 0xbfb8aa3b, v75
	v_exp_f32_e32 v82, v82
	v_exp_f32_e32 v83, v83
	v_exp_f32_e32 v84, v84
	v_exp_f32_e32 v85, v85
	v_exp_f32_e32 v86, v86
	v_exp_f32_e32 v87, v87
	v_exp_f32_e32 v88, v88
	v_exp_f32_e32 v89, v89
	v_add_f32_e32 v82, 1.0, v82
	v_add_f32_e32 v83, 1.0, v83
	v_add_f32_e32 v84, 1.0, v84
	v_add_f32_e32 v85, 1.0, v85
	v_add_f32_e32 v86, 1.0, v86
	v_add_f32_e32 v87, 1.0, v87
	v_add_f32_e32 v88, 1.0, v88
	v_add_f32_e32 v89, 1.0, v89
	v_rcp_f32_e32 v82, v82
	v_rcp_f32_e32 v83, v83
	v_rcp_f32_e32 v84, v84
	v_rcp_f32_e32 v85, v85
	v_rcp_f32_e32 v86, v86
	v_rcp_f32_e32 v87, v87
	v_rcp_f32_e32 v88, v88
	v_rcp_f32_e32 v89, v89
	v_pk_mul_f32 v[76:77], v[76:77], v[82:83]
	v_pk_mul_f32 v[78:79], v[78:79], v[84:85]
	v_pk_mul_f32 v[72:73], v[72:73], v[86:87]
	v_pk_mul_f32 v[74:75], v[74:75], v[88:89]
	v_pk_mul_f32 v[68:69], v[68:69], v[76:77]
	v_pk_mul_f32 v[70:71], v[70:71], v[78:79]
	v_pk_mul_f32 v[72:73], v[64:65], v[72:73]
	v_pk_mul_f32 v[74:75], v[66:67], v[74:75]
	v_cvt_pk_bf16_f32 v64, v68, v69
	v_cvt_pk_bf16_f32 v65, v70, v71
	v_cvt_pk_bf16_f32 v66, v72, v73
	v_cvt_pk_bf16_f32 v67, v74, v75
	global_store_dwordx4 v[80:81], v[64:67], off
	global_load_dword v238, v[146:147], off
	s_nop 0
	v_add_u32_e32 v65, 0x80, v140
	s_nop 1
	v_mov_b32_e32 v64, v234
	v_fmamk_f32 v64, v64, 0x3a000000, v154
	v_mul_f32_e32 v66, 0x4b800000, v64
	v_cmp_gt_f32_e32 vcc, s60, v64
	s_nop 1
	v_cndmask_b32_e32 v64, v64, v66, vcc
	v_rsq_f32_e32 v66, v64
	v_mad_i64_i32 v[64:65], s[0:1], v65, s51, v[142:143]
	v_lshl_add_u64 v[64:65], v[64:65], 0, v[144:145]
	v_mul_f32_e32 v67, 0x45800000, v66
	v_cndmask_b32_e32 v66, v66, v67, vcc
; __device__ __forceinline__ unsigned cvt_pk_bf16(float lo, float hi) { const f32x2 v = {lo, hi}; return __builtin_bit_cast(unsigned, __builtin_convertvector(v, bf16x2_t)); }
; __device__ __forceinline__ float silu_f(float v) { return v * fast_rcp(1.0f + __expf(-v)); }
;     __device__ __forceinline__ void operator()(const f32x4 (&acc)[2][2][4][2], const Unit& u, int wr, int wc, int fr, int fq) const {
;         const int row0 = u.pm * 256 + wr * 64 + fr, col0 = u.pn * 128 + wc * 32 + 8 * fq;
; #pragma unroll
;         for (int ai = 0; ai < 2; ++ai)
; #pragma unroll
;             for (int m = 0; m < 4; ++m) {
;                 bf16_t* rowp = O + (size_t)(row0 + ai * 128 + m * 16) * ldc + col0;
;                 const float rs = ssq ? rsqrtf(ssq[row0 + ai * 128 + m * 16] * (1.0f / DM) + 1e-6f) : 1.0f;
;                 float v[8];
; #pragma unroll
;                 for (int n = 0; n < 2; ++n)
; #pragma unroll
;                     for (int j = 0; j < 4; ++j) v[n * 4 + j] = silu_f(acc[ai][0][m][n][j] * rs) * (acc[ai][1][m][n][j] * rs);
;                 u32x4 w; w.x = cvt_pk_bf16(v[0], v[1]); w.y = cvt_pk_bf16(v[2], v[3]); w.z = cvt_pk_bf16(v[4], v[5]); w.w = cvt_pk_bf16(v[6], v[7]);
;                 *(u32x4*)rowp = w;
;             }
;     }
	v_pk_mul_f32 v[60:61], v[60:61], v[66:67] op_sel_hi:[1,0]
	v_pk_mul_f32 v[62:63], v[62:63], v[66:67] op_sel_hi:[1,0]
	v_pk_mul_f32 v[56:57], v[56:57], v[66:67] op_sel_hi:[1,0]
	v_pk_mul_f32 v[58:59], v[58:59], v[66:67] op_sel_hi:[1,0]
	v_pk_mul_f32 v[52:53], v[52:53], v[66:67] op_sel_hi:[1,0]
	v_pk_mul_f32 v[54:55], v[54:55], v[66:67] op_sel_hi:[1,0]
	v_pk_mul_f32 v[48:49], v[48:49], v[66:67] op_sel_hi:[1,0]
	v_pk_mul_f32 v[50:51], v[50:51], v[66:67] op_sel_hi:[1,0]
	v_mul_f32_e32 v66, 0xbfb8aa3b, v60
	v_mul_f32_e32 v67, 0xbfb8aa3b, v61
	v_mul_f32_e32 v68, 0xbfb8aa3b, v62
	v_mul_f32_e32 v69, 0xbfb8aa3b, v63
	v_mul_f32_e32 v70, 0xbfb8aa3b, v56
	v_mul_f32_e32 v71, 0xbfb8aa3b, v57
	v_mul_f32_e32 v72, 0xbfb8aa3b, v58
	v_mul_f32_e32 v73, 0xbfb8aa3b, v59
	v_exp_f32_e32 v66, v66
	v_exp_f32_e32 v67, v67
	v_exp_f32_e32 v68, v68
	v_exp_f32_e32 v69, v69
	v_exp_f32_e32 v70, v70
	v_exp_f32_e32 v71, v71
	v_exp_f32_e32 v72, v72
	v_exp_f32_e32 v73, v73
	v_add_f32_e32 v66, 1.0, v66
	v_add_f32_e32 v67, 1.0, v67
	v_add_f32_e32 v68, 1.0, v68
	v_add_f32_e32 v69, 1.0, v69
	v_add_f32_e32 v70, 1.0, v70
	v_add_f32_e32 v71, 1.0, v71
	v_add_f32_e32 v72, 1.0, v72
	v_add_f32_e32 v73, 1.0, v73
	v_rcp_f32_e32 v66, v66
	v_rcp_f32_e32 v67, v67
	v_rcp_f32_e32 v68, v68
	v_rcp_f32_e32 v69, v69
	v_rcp_f32_e32 v70, v70
	v_rcp_f32_e32 v71, v71
	v_rcp_f32_e32 v72, v72
	v_rcp_f32_e32 v73, v73
	v_pk_mul_f32 v[60:61], v[60:61], v[66:67]
	v_pk_mul_f32 v[62:63], v[62:63], v[68:69]
	v_pk_mul_f32 v[56:57], v[56:57], v[70:71]
	v_pk_mul_f32 v[58:59], v[58:59], v[72:73]
	v_pk_mul_f32 v[52:53], v[52:53], v[60:61]
	v_pk_mul_f32 v[54:55], v[54:55], v[62:63]
	v_pk_mul_f32 v[56:57], v[48:49], v[56:57]
	v_pk_mul_f32 v[58:59], v[50:51], v[58:59]
	v_cvt_pk_bf16_f32 v48, v52, v53
	v_cvt_pk_bf16_f32 v49, v54, v55
	v_cvt_pk_bf16_f32 v50, v56, v57
	v_cvt_pk_bf16_f32 v51, v58, v59
	global_store_dwordx4 v[64:65], v[48:51], off
	global_load_dword v238, v[146:147], off
	s_nop 0
	v_add_u32_e32 v49, 0x90, v140
	s_nop 1
	v_mov_b32_e32 v48, v235
	v_fmamk_f32 v48, v48, 0x3a000000, v154
	v_mul_f32_e32 v50, 0x4b800000, v48
	v_cmp_gt_f32_e32 vcc, s60, v48
	s_nop 1
	v_cndmask_b32_e32 v48, v48, v50, vcc
	v_rsq_f32_e32 v50, v48
	v_mad_i64_i32 v[48:49], s[0:1], v49, s51, v[142:143]
	v_lshl_add_u64 v[48:49], v[48:49], 0, v[144:145]
	v_mul_f32_e32 v51, 0x45800000, v50
	v_cndmask_b32_e32 v50, v50, v51, vcc
	v_pk_mul_f32 v[44:45], v[44:45], v[50:51] op_sel_hi:[1,0]
	v_pk_mul_f32 v[46:47], v[46:47], v[50:51] op_sel_hi:[1,0]
	v_pk_mul_f32 v[40:41], v[40:41], v[50:51] op_sel_hi:[1,0]
	v_pk_mul_f32 v[42:43], v[42:43], v[50:51] op_sel_hi:[1,0]
	v_pk_mul_f32 v[36:37], v[36:37], v[50:51] op_sel_hi:[1,0]
	v_pk_mul_f32 v[38:39], v[38:39], v[50:51] op_sel_hi:[1,0]
	v_pk_mul_f32 v[32:33], v[32:33], v[50:51] op_sel_hi:[1,0]
	v_pk_mul_f32 v[34:35], v[34:35], v[50:51] op_sel_hi:[1,0]
	v_mul_f32_e32 v50, 0xbfb8aa3b, v44
	v_mul_f32_e32 v51, 0xbfb8aa3b, v45
	v_mul_f32_e32 v52, 0xbfb8aa3b, v46
	v_mul_f32_e32 v53, 0xbfb8aa3b, v47
	v_mul_f32_e32 v54, 0xbfb8aa3b, v40
	v_mul_f32_e32 v55, 0xbfb8aa3b, v41
	v_mul_f32_e32 v56, 0xbfb8aa3b, v42
	v_mul_f32_e32 v57, 0xbfb8aa3b, v43
	v_exp_f32_e32 v50, v50
	v_exp_f32_e32 v51, v51
	v_exp_f32_e32 v52, v52
	v_exp_f32_e32 v53, v53
	v_exp_f32_e32 v54, v54
	v_exp_f32_e32 v55, v55
	v_exp_f32_e32 v56, v56
	v_exp_f32_e32 v57, v57
	v_add_f32_e32 v50, 1.0, v50
	v_add_f32_e32 v51, 1.0, v51
	v_add_f32_e32 v52, 1.0, v52
	v_add_f32_e32 v53, 1.0, v53
	v_add_f32_e32 v54, 1.0, v54
	v_add_f32_e32 v55, 1.0, v55
	v_add_f32_e32 v56, 1.0, v56
	v_add_f32_e32 v57, 1.0, v57
	v_rcp_f32_e32 v50, v50
	v_rcp_f32_e32 v51, v51
	v_rcp_f32_e32 v52, v52
	v_rcp_f32_e32 v53, v53
	v_rcp_f32_e32 v54, v54
	v_rcp_f32_e32 v55, v55
	v_rcp_f32_e32 v56, v56
	v_rcp_f32_e32 v57, v57
	v_pk_mul_f32 v[44:45], v[44:45], v[50:51]
	v_pk_mul_f32 v[46:47], v[46:47], v[52:53]
	v_pk_mul_f32 v[40:41], v[40:41], v[54:55]
	v_pk_mul_f32 v[42:43], v[42:43], v[56:57]
	v_pk_mul_f32 v[36:37], v[36:37], v[44:45]
	v_pk_mul_f32 v[38:39], v[38:39], v[46:47]
	v_pk_mul_f32 v[40:41], v[32:33], v[40:41]
	v_pk_mul_f32 v[42:43], v[34:35], v[42:43]
	v_cvt_pk_bf16_f32 v32, v36, v37
	v_cvt_pk_bf16_f32 v33, v38, v39
	v_cvt_pk_bf16_f32 v34, v40, v41
	v_cvt_pk_bf16_f32 v35, v42, v43
	global_store_dwordx4 v[48:49], v[32:35], off
	global_load_dword v238, v[146:147], off
	s_nop 0
	v_add_u32_e32 v33, 0xa0, v140
	s_nop 1
	v_mov_b32_e32 v32, v236
	v_fmamk_f32 v32, v32, 0x3a000000, v154
	v_mul_f32_e32 v34, 0x4b800000, v32
	v_cmp_gt_f32_e32 vcc, s60, v32
	s_nop 1
	v_cndmask_b32_e32 v32, v32, v34, vcc
	v_rsq_f32_e32 v34, v32
; __device__ __forceinline__ unsigned cvt_pk_bf16(float lo, float hi) { const f32x2 v = {lo, hi}; return __builtin_bit_cast(unsigned, __builtin_convertvector(v, bf16x2_t)); }
; __device__ __forceinline__ float silu_f(float v) { return v * fast_rcp(1.0f + __expf(-v)); }
; #define PG8_BAR __builtin_amdgcn_s_barrier()
; template <class Epi, class Sched>
; __device__ __forceinline__ void gemm_phase(LAS unsigned char* lds, const int K, const Sched& S, const Epi& E) {
;     ...
;         if (wr == 0) PG8_BAR;
;         E(acc, cur, wr, wc, fr, fq);
;         if (!has_next) break;
; #pragma unroll
;         for (int a = 0; a < 2; ++a)
; #pragma unroll
;             for (int b = 0; b < 2; ++b)
; #pragma unroll
;                 for (int m = 0; m < 4; ++m)
; #pragma unroll
;                     for (int n = 0; n < 2; ++n) acc[a][b][m][n] = (f32x4){0.f, 0.f, 0.f, 0.f};
;         cur = nxt; cA = nA; cB = nB; ++ui;
;         if (wr == 1) PG8_BAR;
;     }
;     __device__ __forceinline__ void operator()(const f32x4 (&acc)[2][2][4][2], const Unit& u, int wr, int wc, int fr, int fq) const {
;         const int row0 = u.pm * 256 + wr * 64 + fr, col0 = u.pn * 128 + wc * 32 + 8 * fq;
; #pragma unroll
;         for (int ai = 0; ai < 2; ++ai)
; #pragma unroll
;             for (int m = 0; m < 4; ++m) {
;                 bf16_t* rowp = O + (size_t)(row0 + ai * 128 + m * 16) * ldc + col0;
;                 const float rs = ssq ? rsqrtf(ssq[row0 + ai * 128 + m * 16] * (1.0f / DM) + 1e-6f) : 1.0f;
;                 float v[8];
; #pragma unroll
;                 for (int n = 0; n < 2; ++n)
; #pragma unroll
;                     for (int j = 0; j < 4; ++j) v[n * 4 + j] = silu_f(acc[ai][0][m][n][j] * rs) * (acc[ai][1][m][n][j] * rs);
;                 u32x4 w; w.x = cvt_pk_bf16(v[0], v[1]); w.y = cvt_pk_bf16(v[2], v[3]); w.z = cvt_pk_bf16(v[4], v[5]); w.w = cvt_pk_bf16(v[6], v[7]);
;                 *(u32x4*)rowp = w;
;             }
;     }
	v_mad_i64_i32 v[32:33], s[0:1], v33, s51, v[142:143]
	v_lshl_add_u64 v[32:33], v[32:33], 0, v[144:145]
	v_mul_f32_e32 v35, 0x45800000, v34
	v_cndmask_b32_e32 v34, v34, v35, vcc
	v_pk_mul_f32 v[28:29], v[28:29], v[34:35] op_sel_hi:[1,0]
	v_pk_mul_f32 v[30:31], v[30:31], v[34:35] op_sel_hi:[1,0]
	v_pk_mul_f32 v[24:25], v[24:25], v[34:35] op_sel_hi:[1,0]
	v_pk_mul_f32 v[26:27], v[26:27], v[34:35] op_sel_hi:[1,0]
	v_pk_mul_f32 v[20:21], v[20:21], v[34:35] op_sel_hi:[1,0]
	v_pk_mul_f32 v[22:23], v[22:23], v[34:35] op_sel_hi:[1,0]
	v_pk_mul_f32 v[16:17], v[16:17], v[34:35] op_sel_hi:[1,0]
	v_pk_mul_f32 v[18:19], v[18:19], v[34:35] op_sel_hi:[1,0]
	v_mul_f32_e32 v34, 0xbfb8aa3b, v28
	v_mul_f32_e32 v35, 0xbfb8aa3b, v29
	v_mul_f32_e32 v36, 0xbfb8aa3b, v30
	v_mul_f32_e32 v37, 0xbfb8aa3b, v31
	v_mul_f32_e32 v38, 0xbfb8aa3b, v24
	v_mul_f32_e32 v39, 0xbfb8aa3b, v25
	v_mul_f32_e32 v40, 0xbfb8aa3b, v26
	v_mul_f32_e32 v41, 0xbfb8aa3b, v27
	v_exp_f32_e32 v34, v34
	v_exp_f32_e32 v35, v35
	v_exp_f32_e32 v36, v36
	v_exp_f32_e32 v37, v37
	v_exp_f32_e32 v38, v38
	v_exp_f32_e32 v39, v39
	v_exp_f32_e32 v40, v40
	v_exp_f32_e32 v41, v41
	v_add_f32_e32 v34, 1.0, v34
	v_add_f32_e32 v35, 1.0, v35
	v_add_f32_e32 v36, 1.0, v36
	v_add_f32_e32 v37, 1.0, v37
	v_add_f32_e32 v38, 1.0, v38
	v_add_f32_e32 v39, 1.0, v39
	v_add_f32_e32 v40, 1.0, v40
	v_add_f32_e32 v41, 1.0, v41
	v_rcp_f32_e32 v34, v34
	v_rcp_f32_e32 v35, v35
	v_rcp_f32_e32 v36, v36
	v_rcp_f32_e32 v37, v37
	v_rcp_f32_e32 v38, v38
	v_rcp_f32_e32 v39, v39
	v_rcp_f32_e32 v40, v40
	v_rcp_f32_e32 v41, v41
	v_pk_mul_f32 v[28:29], v[28:29], v[34:35]
	v_pk_mul_f32 v[30:31], v[30:31], v[36:37]
	v_pk_mul_f32 v[24:25], v[24:25], v[38:39]
	v_pk_mul_f32 v[26:27], v[26:27], v[40:41]
	v_pk_mul_f32 v[20:21], v[20:21], v[28:29]
	v_pk_mul_f32 v[22:23], v[22:23], v[30:31]
	v_pk_mul_f32 v[24:25], v[16:17], v[24:25]
	v_pk_mul_f32 v[26:27], v[18:19], v[26:27]
	v_cvt_pk_bf16_f32 v16, v20, v21
	v_cvt_pk_bf16_f32 v17, v22, v23
	v_cvt_pk_bf16_f32 v18, v24, v25
	v_cvt_pk_bf16_f32 v19, v26, v27
	global_store_dwordx4 v[32:33], v[16:19], off
	global_load_dword v238, v[146:147], off
	s_and_b64 vcc, exec, s[4:5]
	v_add_u32_e32 v17, 0xb0, v140
	s_nop 1
	v_mov_b32_e32 v16, v237
	v_fmamk_f32 v16, v16, 0x3a000000, v154
	v_mul_f32_e32 v18, 0x4b800000, v16
	v_cmp_gt_f32_e64 s[0:1], s60, v16
	s_nop 1
	v_cndmask_b32_e64 v16, v16, v18, s[0:1]
	v_rsq_f32_e32 v18, v16
	v_mad_i64_i32 v[16:17], s[4:5], v17, s51, v[142:143]
	v_lshl_add_u64 v[16:17], v[16:17], 0, v[144:145]
	v_mul_f32_e32 v19, 0x45800000, v18
	v_cndmask_b32_e64 v18, v18, v19, s[0:1]
	v_pk_mul_f32 v[12:13], v[12:13], v[18:19] op_sel_hi:[1,0]
	v_pk_mul_f32 v[14:15], v[14:15], v[18:19] op_sel_hi:[1,0]
	v_pk_mul_f32 v[8:9], v[8:9], v[18:19] op_sel_hi:[1,0]
	v_pk_mul_f32 v[10:11], v[10:11], v[18:19] op_sel_hi:[1,0]
	v_pk_mul_f32 v[4:5], v[4:5], v[18:19] op_sel_hi:[1,0]
	v_pk_mul_f32 v[6:7], v[6:7], v[18:19] op_sel_hi:[1,0]
	v_pk_mul_f32 v[0:1], v[0:1], v[18:19] op_sel_hi:[1,0]
	v_pk_mul_f32 v[2:3], v[2:3], v[18:19] op_sel_hi:[1,0]
	v_mul_f32_e32 v18, 0xbfb8aa3b, v12
	v_mul_f32_e32 v19, 0xbfb8aa3b, v13
	v_mul_f32_e32 v20, 0xbfb8aa3b, v14
	v_mul_f32_e32 v21, 0xbfb8aa3b, v15
	v_mul_f32_e32 v22, 0xbfb8aa3b, v8
	v_mul_f32_e32 v23, 0xbfb8aa3b, v9
	v_mul_f32_e32 v24, 0xbfb8aa3b, v10
	v_mul_f32_e32 v25, 0xbfb8aa3b, v11
	v_exp_f32_e32 v18, v18
	v_exp_f32_e32 v19, v19
	v_exp_f32_e32 v20, v20
	v_exp_f32_e32 v21, v21
	v_exp_f32_e32 v22, v22
	v_exp_f32_e32 v23, v23
	v_exp_f32_e32 v24, v24
	v_exp_f32_e32 v25, v25
	v_add_f32_e32 v18, 1.0, v18
	v_add_f32_e32 v19, 1.0, v19
	v_add_f32_e32 v20, 1.0, v20
	v_add_f32_e32 v21, 1.0, v21
	v_add_f32_e32 v22, 1.0, v22
	v_add_f32_e32 v23, 1.0, v23
	v_add_f32_e32 v24, 1.0, v24
	v_add_f32_e32 v25, 1.0, v25
	v_rcp_f32_e32 v18, v18
	v_rcp_f32_e32 v19, v19
	v_rcp_f32_e32 v20, v20
	v_rcp_f32_e32 v21, v21
	v_rcp_f32_e32 v22, v22
	v_rcp_f32_e32 v23, v23
	v_rcp_f32_e32 v24, v24
	v_rcp_f32_e32 v25, v25
	v_pk_mul_f32 v[12:13], v[12:13], v[18:19]
	v_pk_mul_f32 v[14:15], v[14:15], v[20:21]
	v_pk_mul_f32 v[8:9], v[8:9], v[22:23]
	v_pk_mul_f32 v[10:11], v[10:11], v[24:25]
	v_pk_mul_f32 v[4:5], v[4:5], v[12:13]
	v_pk_mul_f32 v[6:7], v[6:7], v[14:15]
	v_pk_mul_f32 v[8:9], v[0:1], v[8:9]
	v_pk_mul_f32 v[10:11], v[2:3], v[10:11]
	v_cvt_pk_bf16_f32 v0, v4, v5
	v_cvt_pk_bf16_f32 v1, v6, v7
	v_cvt_pk_bf16_f32 v2, v8, v9
	v_cvt_pk_bf16_f32 v3, v10, v11
	s_mov_b64 s[0:1], -1
	global_store_dwordx4 v[16:17], v[0:3], off
	s_cbranch_vccnz .LBB0_1427
	s_andn2_b64 vcc, exec, s[10:11]
	s_cbranch_vccnz .LBB0_1426
	s_barrier
	s_branch .LBB0_1426
